# in-proj K loop as register-staged compute/load ping-pong: 4x[load seg|barrier|16 MFMA prio1|barrier] per K-step, waves 4-7 one barrier behind
# baseline (speedup 1.0000x reference)
; template <int EPI>
; DI void gemm_phase(const P& p, int l, const u16* __restrict__ A, const u16* __restrict__ Bt, int mpx, char* lds) {
;     ...
;   {
;   const int lane = tid & 63, w = tid >> 6, r = lane & 15, g = lane >> 4, wm = w >> 2, wn = w & 3;
;   __syncthreads();
;   GLOAD(Ag, Bg, 64)
;   __builtin_amdgcn_sched_barrier(0);
;   GCOMPUTE_KS(As0, Bs0, 0)
;   __builtin_amdgcn_sched_barrier(0);
;   GSTORE(As1, Bs1)
;   GLOAD(Ag, Bg, 128)
;   __builtin_amdgcn_sched_barrier(0);
;   GCOMPUTE_KS(As0, Bs0, 1)
;   __builtin_amdgcn_sched_barrier(0);
.LBB0_81:
	s_mov_b32 s57, s3
	s_lshl_b64 s[42:43], s[56:57], 11
	s_lshl_b32 s2, s51, 11
	s_add_u32 s58, s16, s42
	s_addc_u32 s59, s17, s43
	s_add_u32 s60, s24, s2
	s_addc_u32 s61, s25, 0
	v_add_u32_e32 v208, s33, v196
	v_add_u32_e32 v209, s35, v196
	v_add_u32_e32 v210, s39, v196
	global_load_dwordx4 v[162:165], v196, s[40:41] offset:128
	global_load_dwordx4 v[166:169], v208, s[40:41] offset:128
	global_load_dwordx4 v[170:173], v209, s[40:41] offset:128
	global_load_dwordx4 v[174:177], v210, s[40:41] offset:128
	global_load_dwordx4 v[178:181], v196, s[0:1] offset:128
	global_load_dwordx4 v[182:185], v208, s[0:1] offset:128
	global_load_dwordx4 v[186:189], v209, s[0:1] offset:128
	global_load_dwordx4 v[190:193], v210, s[0:1] offset:128
	s_waitcnt lgkmcnt(0)
	s_barrier
	v_readfirstlane_b32 s71, v195
	s_cmp_lt_u32 s71, 0x100
	s_cbranch_scc1 .Lhb_in0
	s_barrier
.Lhb_in0:
	ds_read_b128 v[212:215], v204 offset:32768
	ds_read_b128 v[216:219], v204 offset:34816
	ds_read_b128 v[220:223], v204 offset:36864
	ds_read_b128 v[234:237], v204 offset:38912
	ds_read_b128 v[238:241], v205
	ds_read_b128 v[242:245], v205 offset:2048
	ds_read_b128 v[246:249], v205 offset:4096
	ds_read_b128 v[250:253], v205 offset:6144
	global_load_dwordx4 v[130:133], v196, s[40:41] offset:256
	global_load_dwordx4 v[134:137], v208, s[40:41] offset:256
	s_waitcnt vmcnt(9)
	ds_write_b128 v202, v[162:165]
	s_waitcnt vmcnt(8)
	ds_write_b128 v227, v[166:169]
	s_waitcnt lgkmcnt(0)
	s_barrier
	s_setprio 1
	v_mfma_f32_16x16x32_bf16 v[6:9], v[238:241], v[212:215], 0
	v_mfma_f32_16x16x32_bf16 v[10:13], v[238:241], v[216:219], 0
	v_mfma_f32_16x16x32_bf16 v[14:17], v[238:241], v[220:223], 0
	v_mfma_f32_16x16x32_bf16 v[18:21], v[238:241], v[234:237], 0
	v_mfma_f32_16x16x32_bf16 v[22:25], v[242:245], v[212:215], 0
	v_mfma_f32_16x16x32_bf16 v[26:29], v[242:245], v[216:219], 0
	v_mfma_f32_16x16x32_bf16 v[30:33], v[242:245], v[220:223], 0
	v_mfma_f32_16x16x32_bf16 v[34:37], v[242:245], v[234:237], 0
	v_mfma_f32_16x16x32_bf16 v[38:41], v[246:249], v[212:215], 0
	v_mfma_f32_16x16x32_bf16 v[42:45], v[246:249], v[216:219], 0
	v_mfma_f32_16x16x32_bf16 v[46:49], v[246:249], v[220:223], 0
	v_mfma_f32_16x16x32_bf16 v[50:53], v[246:249], v[234:237], 0
	v_mfma_f32_16x16x32_bf16 v[54:57], v[250:253], v[212:215], 0
	v_mfma_f32_16x16x32_bf16 v[58:61], v[250:253], v[216:219], 0
	v_mfma_f32_16x16x32_bf16 v[62:65], v[250:253], v[220:223], 0
	v_mfma_f32_16x16x32_bf16 v[66:69], v[250:253], v[234:237], 0
	s_setprio 0
	s_barrier
	ds_read_b128 v[238:241], v205 offset:8192
	ds_read_b128 v[242:245], v205 offset:10240
	ds_read_b128 v[246:249], v205 offset:12288
	ds_read_b128 v[250:253], v205 offset:14336
	global_load_dwordx4 v[138:141], v209, s[40:41] offset:256
	global_load_dwordx4 v[142:145], v210, s[40:41] offset:256
	s_waitcnt vmcnt(9)
	ds_write_b128 v228, v[170:173]
	s_waitcnt vmcnt(8)
	ds_write_b128 v229, v[174:177]
	s_waitcnt lgkmcnt(0)
	s_barrier
	s_setprio 1
	v_mfma_f32_16x16x32_bf16 v[70:73], v[238:241], v[212:215], 0
	v_mfma_f32_16x16x32_bf16 v[74:77], v[238:241], v[216:219], 0
	v_mfma_f32_16x16x32_bf16 v[78:81], v[238:241], v[220:223], 0
	v_mfma_f32_16x16x32_bf16 v[82:85], v[238:241], v[234:237], 0
	v_mfma_f32_16x16x32_bf16 v[86:89], v[242:245], v[212:215], 0
	v_mfma_f32_16x16x32_bf16 v[90:93], v[242:245], v[216:219], 0
	v_mfma_f32_16x16x32_bf16 v[94:97], v[242:245], v[220:223], 0
	v_mfma_f32_16x16x32_bf16 v[98:101], v[242:245], v[234:237], 0
	v_mfma_f32_16x16x32_bf16 v[102:105], v[246:249], v[212:215], 0
	v_mfma_f32_16x16x32_bf16 v[106:109], v[246:249], v[216:219], 0
	v_mfma_f32_16x16x32_bf16 v[110:113], v[246:249], v[220:223], 0
	v_mfma_f32_16x16x32_bf16 v[114:117], v[246:249], v[234:237], 0
	v_mfma_f32_16x16x32_bf16 v[118:121], v[250:253], v[212:215], 0
	v_mfma_f32_16x16x32_bf16 v[122:125], v[250:253], v[216:219], 0
	v_mfma_f32_16x16x32_bf16 v[126:129], v[250:253], v[220:223], 0
	v_mfma_f32_16x16x32_bf16 v[2:5], v[250:253], v[234:237], 0
	s_setprio 0
	s_barrier
	ds_read_b128 v[162:165], v206 offset:32768
	ds_read_b128 v[166:169], v206 offset:34816
	ds_read_b128 v[170:173], v206 offset:36864
	ds_read_b128 v[174:177], v206 offset:38912
	ds_read_b128 v[238:241], v207
	ds_read_b128 v[242:245], v207 offset:2048
	ds_read_b128 v[246:249], v207 offset:4096
	ds_read_b128 v[250:253], v207 offset:6144
	global_load_dwordx4 v[146:149], v196, s[0:1] offset:256
	global_load_dwordx4 v[150:153], v208, s[0:1] offset:256
	s_waitcnt vmcnt(9)
	ds_write_b128 v203, v[178:181]
	s_waitcnt vmcnt(8)
	ds_write_b128 v230, v[182:185]
	s_waitcnt lgkmcnt(0)
	s_barrier
	s_setprio 1
	v_mfma_f32_16x16x32_bf16 v[6:9], v[238:241], v[162:165], v[6:9]
	v_mfma_f32_16x16x32_bf16 v[10:13], v[238:241], v[166:169], v[10:13]
	v_mfma_f32_16x16x32_bf16 v[14:17], v[238:241], v[170:173], v[14:17]
	v_mfma_f32_16x16x32_bf16 v[18:21], v[238:241], v[174:177], v[18:21]
	v_mfma_f32_16x16x32_bf16 v[22:25], v[242:245], v[162:165], v[22:25]
	v_mfma_f32_16x16x32_bf16 v[26:29], v[242:245], v[166:169], v[26:29]
	v_mfma_f32_16x16x32_bf16 v[30:33], v[242:245], v[170:173], v[30:33]
	v_mfma_f32_16x16x32_bf16 v[34:37], v[242:245], v[174:177], v[34:37]
	v_mfma_f32_16x16x32_bf16 v[38:41], v[246:249], v[162:165], v[38:41]
	v_mfma_f32_16x16x32_bf16 v[42:45], v[246:249], v[166:169], v[42:45]
	v_mfma_f32_16x16x32_bf16 v[46:49], v[246:249], v[170:173], v[46:49]
	v_mfma_f32_16x16x32_bf16 v[50:53], v[246:249], v[174:177], v[50:53]
	v_mfma_f32_16x16x32_bf16 v[54:57], v[250:253], v[162:165], v[54:57]
	v_mfma_f32_16x16x32_bf16 v[58:61], v[250:253], v[166:169], v[58:61]
	v_mfma_f32_16x16x32_bf16 v[62:65], v[250:253], v[170:173], v[62:65]
	v_mfma_f32_16x16x32_bf16 v[66:69], v[250:253], v[174:177], v[66:69]
	s_setprio 0
	s_barrier
; #define GCOMPUTE(AS, BS) GCOMPUTE_KS(AS, BS, 0) GCOMPUTE_KS(AS, BS, 1)
; template <int EPI>
; DI void gemm_phase(const P& p, int l, const u16* __restrict__ A, const u16* __restrict__ Bt, int mpx, char* lds) {
;     ...
;   GLOAD(Ag, Bg, 128)
;   __builtin_amdgcn_sched_barrier(0);
;   GCOMPUTE_KS(As0, Bs0, 1)
;   __builtin_amdgcn_sched_barrier(0);
; #pragma unroll 1
;   for (int kk = 1; kk < 15; kk += 2) {
;     __syncthreads();
;     GSTORE(As0, Bs0)
;     GLOAD(Ag, Bg, (kk + 2) * 64)
;     __builtin_amdgcn_sched_barrier(0);
;     GCOMPUTE(As1, Bs1)
;     __builtin_amdgcn_sched_barrier(0);
	ds_read_b128 v[238:241], v207 offset:8192
	ds_read_b128 v[242:245], v207 offset:10240
	ds_read_b128 v[246:249], v207 offset:12288
	ds_read_b128 v[250:253], v207 offset:14336
	global_load_dwordx4 v[154:157], v209, s[0:1] offset:256
	global_load_dwordx4 v[158:161], v210, s[0:1] offset:256
	s_waitcnt vmcnt(9)
	ds_write_b128 v231, v[186:189]
	s_waitcnt vmcnt(8)
	ds_write_b128 v232, v[190:193]
	s_waitcnt lgkmcnt(0)
	s_barrier
	s_setprio 1
	v_mfma_f32_16x16x32_bf16 v[70:73], v[238:241], v[162:165], v[70:73]
	v_mfma_f32_16x16x32_bf16 v[74:77], v[238:241], v[166:169], v[74:77]
	v_mfma_f32_16x16x32_bf16 v[78:81], v[238:241], v[170:173], v[78:81]
	v_mfma_f32_16x16x32_bf16 v[82:85], v[238:241], v[174:177], v[82:85]
	v_mfma_f32_16x16x32_bf16 v[86:89], v[242:245], v[162:165], v[86:89]
	v_mfma_f32_16x16x32_bf16 v[90:93], v[242:245], v[166:169], v[90:93]
	v_mfma_f32_16x16x32_bf16 v[94:97], v[242:245], v[170:173], v[94:97]
	v_mfma_f32_16x16x32_bf16 v[98:101], v[242:245], v[174:177], v[98:101]
	v_mfma_f32_16x16x32_bf16 v[102:105], v[246:249], v[162:165], v[102:105]
	v_mfma_f32_16x16x32_bf16 v[106:109], v[246:249], v[166:169], v[106:109]
	v_mfma_f32_16x16x32_bf16 v[110:113], v[246:249], v[170:173], v[110:113]
	v_mfma_f32_16x16x32_bf16 v[114:117], v[246:249], v[174:177], v[114:117]
	v_mfma_f32_16x16x32_bf16 v[118:121], v[250:253], v[162:165], v[118:121]
	v_mfma_f32_16x16x32_bf16 v[122:125], v[250:253], v[166:169], v[122:125]
	v_mfma_f32_16x16x32_bf16 v[126:129], v[250:253], v[170:173], v[126:129]
	v_mfma_f32_16x16x32_bf16 v[2:5], v[250:253], v[174:177], v[2:5]
	s_setprio 0
	s_barrier
	s_mov_b32 s49, 1
	s_movk_i32 s47, 0x100
	s_mov_b64 s[42:43], s[0:1]
	s_mov_b64 s[44:45], s[40:41]
.LBB0_82:
	s_add_i32 s48, s49, 2
	ds_read_b128 v[212:215], v198
	ds_read_b128 v[216:219], v198 offset:2048
	ds_read_b128 v[220:223], v198 offset:4096
	ds_read_b128 v[234:237], v198 offset:6144
	ds_read_b128 v[238:241], v199
	ds_read_b128 v[242:245], v199 offset:2048
	ds_read_b128 v[246:249], v199 offset:4096
	ds_read_b128 v[250:253], v199 offset:6144
	global_load_dwordx4 v[162:165], v196, s[44:45] offset:384
	global_load_dwordx4 v[166:169], v208, s[44:45] offset:384
	s_waitcnt vmcnt(9)
	ds_write_b128 v201, v[130:133]
	s_waitcnt vmcnt(8)
	ds_write_b128 v201, v[134:137] offset:8192
	s_waitcnt lgkmcnt(0)
	s_barrier
	s_setprio 1
	v_mfma_f32_16x16x32_bf16 v[6:9], v[238:241], v[212:215], v[6:9]
	v_mfma_f32_16x16x32_bf16 v[10:13], v[238:241], v[216:219], v[10:13]
	v_mfma_f32_16x16x32_bf16 v[14:17], v[238:241], v[220:223], v[14:17]
	v_mfma_f32_16x16x32_bf16 v[18:21], v[238:241], v[234:237], v[18:21]
	v_mfma_f32_16x16x32_bf16 v[22:25], v[242:245], v[212:215], v[22:25]
	v_mfma_f32_16x16x32_bf16 v[26:29], v[242:245], v[216:219], v[26:29]
	v_mfma_f32_16x16x32_bf16 v[30:33], v[242:245], v[220:223], v[30:33]
	v_mfma_f32_16x16x32_bf16 v[34:37], v[242:245], v[234:237], v[34:37]
	v_mfma_f32_16x16x32_bf16 v[38:41], v[246:249], v[212:215], v[38:41]
	v_mfma_f32_16x16x32_bf16 v[42:45], v[246:249], v[216:219], v[42:45]
	v_mfma_f32_16x16x32_bf16 v[46:49], v[246:249], v[220:223], v[46:49]
	v_mfma_f32_16x16x32_bf16 v[50:53], v[246:249], v[234:237], v[50:53]
	v_mfma_f32_16x16x32_bf16 v[54:57], v[250:253], v[212:215], v[54:57]
	v_mfma_f32_16x16x32_bf16 v[58:61], v[250:253], v[216:219], v[58:61]
	v_mfma_f32_16x16x32_bf16 v[62:65], v[250:253], v[220:223], v[62:65]
	v_mfma_f32_16x16x32_bf16 v[66:69], v[250:253], v[234:237], v[66:69]
	s_setprio 0
	s_barrier
	ds_read_b128 v[238:241], v199 offset:8192
	ds_read_b128 v[242:245], v199 offset:10240
	ds_read_b128 v[246:249], v199 offset:12288
	ds_read_b128 v[250:253], v199 offset:14336
	global_load_dwordx4 v[170:173], v209, s[44:45] offset:384
	global_load_dwordx4 v[174:177], v210, s[44:45] offset:384
	s_waitcnt vmcnt(9)
	ds_write_b128 v201, v[138:141] offset:16384
	s_waitcnt vmcnt(8)
	ds_write_b128 v201, v[142:145] offset:24576
	s_waitcnt lgkmcnt(0)
	s_barrier
	s_setprio 1
	v_mfma_f32_16x16x32_bf16 v[70:73], v[238:241], v[212:215], v[70:73]
	v_mfma_f32_16x16x32_bf16 v[74:77], v[238:241], v[216:219], v[74:77]
	v_mfma_f32_16x16x32_bf16 v[78:81], v[238:241], v[220:223], v[78:81]
	v_mfma_f32_16x16x32_bf16 v[82:85], v[238:241], v[234:237], v[82:85]
	v_mfma_f32_16x16x32_bf16 v[86:89], v[242:245], v[212:215], v[86:89]
	v_mfma_f32_16x16x32_bf16 v[90:93], v[242:245], v[216:219], v[90:93]
	v_mfma_f32_16x16x32_bf16 v[94:97], v[242:245], v[220:223], v[94:97]
	v_mfma_f32_16x16x32_bf16 v[98:101], v[242:245], v[234:237], v[98:101]
	v_mfma_f32_16x16x32_bf16 v[102:105], v[246:249], v[212:215], v[102:105]
	v_mfma_f32_16x16x32_bf16 v[106:109], v[246:249], v[216:219], v[106:109]
	v_mfma_f32_16x16x32_bf16 v[110:113], v[246:249], v[220:223], v[110:113]
	v_mfma_f32_16x16x32_bf16 v[114:117], v[246:249], v[234:237], v[114:117]
	v_mfma_f32_16x16x32_bf16 v[118:121], v[250:253], v[212:215], v[118:121]
	v_mfma_f32_16x16x32_bf16 v[122:125], v[250:253], v[216:219], v[122:125]
	v_mfma_f32_16x16x32_bf16 v[126:129], v[250:253], v[220:223], v[126:129]
	v_mfma_f32_16x16x32_bf16 v[2:5], v[250:253], v[234:237], v[2:5]
	s_setprio 0
	s_barrier
	ds_read_b128 v[130:133], v200
	ds_read_b128 v[134:137], v200 offset:2048
	ds_read_b128 v[138:141], v200 offset:4096
	ds_read_b128 v[142:145], v200 offset:6144
	ds_read_b128 v[238:241], v233
	ds_read_b128 v[242:245], v233 offset:2048
	ds_read_b128 v[246:249], v233 offset:4096
	ds_read_b128 v[250:253], v233 offset:6144
	global_load_dwordx4 v[178:181], v196, s[42:43] offset:384
	global_load_dwordx4 v[182:185], v208, s[42:43] offset:384
	s_waitcnt vmcnt(9)
	ds_write_b128 v201, v[146:149] offset:32768
	s_waitcnt vmcnt(8)
	ds_write_b128 v201, v[150:153] offset:40960
	s_waitcnt lgkmcnt(0)
	s_barrier
; #define GCOMPUTE(AS, BS) GCOMPUTE_KS(AS, BS, 0) GCOMPUTE_KS(AS, BS, 1)
; template <int EPI>
; DI void gemm_phase(const P& p, int l, const u16* __restrict__ A, const u16* __restrict__ Bt, int mpx, char* lds) {
;     ...
;     __syncthreads();
;     GSTORE(As0, Bs0)
;     GLOAD(Ag, Bg, (kk + 2) * 64)
;     __builtin_amdgcn_sched_barrier(0);
;     GCOMPUTE(As1, Bs1)
;     __builtin_amdgcn_sched_barrier(0);
;     __syncthreads();
;     GSTORE(As1, Bs1)
;     {
;       const bool in_tile = kk + 3 < 16;
;       const u16* pa = in_tile ? Ag : Agn;
;       const u16* pb = in_tile ? Bg : Bgn;
;       const int k0 = in_tile ? (kk + 3) * 64 : 0;
;       GLOAD(pa, pb, k0)
;     }
;     __builtin_amdgcn_sched_barrier(0);
;     GCOMPUTE(As0, Bs0)
	s_setprio 1
	v_mfma_f32_16x16x32_bf16 v[6:9], v[238:241], v[130:133], v[6:9]
	v_mfma_f32_16x16x32_bf16 v[10:13], v[238:241], v[134:137], v[10:13]
	v_mfma_f32_16x16x32_bf16 v[14:17], v[238:241], v[138:141], v[14:17]
	v_mfma_f32_16x16x32_bf16 v[18:21], v[238:241], v[142:145], v[18:21]
	v_mfma_f32_16x16x32_bf16 v[22:25], v[242:245], v[130:133], v[22:25]
	v_mfma_f32_16x16x32_bf16 v[26:29], v[242:245], v[134:137], v[26:29]
	v_mfma_f32_16x16x32_bf16 v[30:33], v[242:245], v[138:141], v[30:33]
	v_mfma_f32_16x16x32_bf16 v[34:37], v[242:245], v[142:145], v[34:37]
	v_mfma_f32_16x16x32_bf16 v[38:41], v[246:249], v[130:133], v[38:41]
	v_mfma_f32_16x16x32_bf16 v[42:45], v[246:249], v[134:137], v[42:45]
	v_mfma_f32_16x16x32_bf16 v[46:49], v[246:249], v[138:141], v[46:49]
	v_mfma_f32_16x16x32_bf16 v[50:53], v[246:249], v[142:145], v[50:53]
	v_mfma_f32_16x16x32_bf16 v[54:57], v[250:253], v[130:133], v[54:57]
	v_mfma_f32_16x16x32_bf16 v[58:61], v[250:253], v[134:137], v[58:61]
	v_mfma_f32_16x16x32_bf16 v[62:65], v[250:253], v[138:141], v[62:65]
	v_mfma_f32_16x16x32_bf16 v[66:69], v[250:253], v[142:145], v[66:69]
	s_setprio 0
	s_barrier
	ds_read_b128 v[238:241], v233 offset:8192
	ds_read_b128 v[242:245], v233 offset:10240
	ds_read_b128 v[246:249], v233 offset:12288
	ds_read_b128 v[250:253], v233 offset:14336
	global_load_dwordx4 v[186:189], v209, s[42:43] offset:384
	global_load_dwordx4 v[190:193], v210, s[42:43] offset:384
	s_waitcnt vmcnt(9)
	ds_write_b128 v201, v[154:157] offset:49152
	s_waitcnt vmcnt(8)
	ds_write_b128 v201, v[158:161] offset:57344
	s_waitcnt lgkmcnt(0)
	s_barrier
	s_setprio 1
	v_mfma_f32_16x16x32_bf16 v[70:73], v[238:241], v[130:133], v[70:73]
	v_mfma_f32_16x16x32_bf16 v[74:77], v[238:241], v[134:137], v[74:77]
	v_mfma_f32_16x16x32_bf16 v[78:81], v[238:241], v[138:141], v[78:81]
	v_mfma_f32_16x16x32_bf16 v[82:85], v[238:241], v[142:145], v[82:85]
	v_mfma_f32_16x16x32_bf16 v[86:89], v[242:245], v[130:133], v[86:89]
	v_mfma_f32_16x16x32_bf16 v[90:93], v[242:245], v[134:137], v[90:93]
	v_mfma_f32_16x16x32_bf16 v[94:97], v[242:245], v[138:141], v[94:97]
	v_mfma_f32_16x16x32_bf16 v[98:101], v[242:245], v[142:145], v[98:101]
	v_mfma_f32_16x16x32_bf16 v[102:105], v[246:249], v[130:133], v[102:105]
	v_mfma_f32_16x16x32_bf16 v[106:109], v[246:249], v[134:137], v[106:109]
	v_mfma_f32_16x16x32_bf16 v[110:113], v[246:249], v[138:141], v[110:113]
	v_mfma_f32_16x16x32_bf16 v[114:117], v[246:249], v[142:145], v[114:117]
	v_mfma_f32_16x16x32_bf16 v[118:121], v[250:253], v[130:133], v[118:121]
	v_mfma_f32_16x16x32_bf16 v[122:125], v[250:253], v[134:137], v[122:125]
	v_mfma_f32_16x16x32_bf16 v[126:129], v[250:253], v[138:141], v[126:129]
	v_mfma_f32_16x16x32_bf16 v[2:5], v[250:253], v[142:145], v[2:5]
	s_setprio 0
	s_barrier
	s_cmp_lt_u32 s49, 13
	s_cselect_b64 s[62:63], -1, 0
	s_and_b64 s[62:63], s[62:63], exec
	s_cselect_b32 s2, s47, 0
	s_cselect_b32 s57, s41, s59
	s_cselect_b32 s64, s40, s58
	s_cselect_b32 s67, s1, s61
	s_cselect_b32 s68, s0, s60
	s_lshl_b64 s[62:63], s[2:3], 1
	s_add_u32 s64, s64, s62
	s_addc_u32 s65, s57, s63
	s_add_u32 s62, s68, s62
	s_addc_u32 s63, s67, s63
	ds_read_b128 v[212:215], v204 offset:32768
	ds_read_b128 v[216:219], v204 offset:34816
	ds_read_b128 v[220:223], v204 offset:36864
	ds_read_b128 v[234:237], v204 offset:38912
	ds_read_b128 v[238:241], v205
	ds_read_b128 v[242:245], v205 offset:2048
	ds_read_b128 v[246:249], v205 offset:4096
	ds_read_b128 v[250:253], v205 offset:6144
	global_load_dwordx4 v[130:133], v196, s[64:65]
	global_load_dwordx4 v[134:137], v208, s[64:65]
	s_waitcnt vmcnt(9)
	ds_write_b128 v202, v[162:165]
	s_waitcnt vmcnt(8)
	ds_write_b128 v227, v[166:169]
	s_waitcnt lgkmcnt(0)
	s_barrier
	s_setprio 1
	v_mfma_f32_16x16x32_bf16 v[6:9], v[238:241], v[212:215], v[6:9]
	v_mfma_f32_16x16x32_bf16 v[10:13], v[238:241], v[216:219], v[10:13]
	v_mfma_f32_16x16x32_bf16 v[14:17], v[238:241], v[220:223], v[14:17]
	v_mfma_f32_16x16x32_bf16 v[18:21], v[238:241], v[234:237], v[18:21]
	v_mfma_f32_16x16x32_bf16 v[22:25], v[242:245], v[212:215], v[22:25]
	v_mfma_f32_16x16x32_bf16 v[26:29], v[242:245], v[216:219], v[26:29]
	v_mfma_f32_16x16x32_bf16 v[30:33], v[242:245], v[220:223], v[30:33]
	v_mfma_f32_16x16x32_bf16 v[34:37], v[242:245], v[234:237], v[34:37]
	v_mfma_f32_16x16x32_bf16 v[38:41], v[246:249], v[212:215], v[38:41]
	v_mfma_f32_16x16x32_bf16 v[42:45], v[246:249], v[216:219], v[42:45]
	v_mfma_f32_16x16x32_bf16 v[46:49], v[246:249], v[220:223], v[46:49]
	v_mfma_f32_16x16x32_bf16 v[50:53], v[246:249], v[234:237], v[50:53]
	v_mfma_f32_16x16x32_bf16 v[54:57], v[250:253], v[212:215], v[54:57]
	v_mfma_f32_16x16x32_bf16 v[58:61], v[250:253], v[216:219], v[58:61]
	v_mfma_f32_16x16x32_bf16 v[62:65], v[250:253], v[220:223], v[62:65]
	v_mfma_f32_16x16x32_bf16 v[66:69], v[250:253], v[234:237], v[66:69]
	s_setprio 0
	s_barrier
	ds_read_b128 v[238:241], v205 offset:8192
	ds_read_b128 v[242:245], v205 offset:10240
	ds_read_b128 v[246:249], v205 offset:12288
	ds_read_b128 v[250:253], v205 offset:14336
	global_load_dwordx4 v[138:141], v209, s[64:65]
	global_load_dwordx4 v[142:145], v210, s[64:65]
	s_waitcnt vmcnt(9)
	ds_write_b128 v228, v[170:173]
	s_waitcnt vmcnt(8)
	ds_write_b128 v229, v[174:177]
	s_waitcnt lgkmcnt(0)
	s_barrier
; #define GCOMPUTE(AS, BS) GCOMPUTE_KS(AS, BS, 0) GCOMPUTE_KS(AS, BS, 1)
; template <int EPI>
; DI void gemm_phase(const P& p, int l, const u16* __restrict__ A, const u16* __restrict__ Bt, int mpx, char* lds) {
;     ...
;     __syncthreads();
;     GSTORE(As1, Bs1)
;     {
;       const bool in_tile = kk + 3 < 16;
;       const u16* pa = in_tile ? Ag : Agn;
;       const u16* pb = in_tile ? Bg : Bgn;
;       const int k0 = in_tile ? (kk + 3) * 64 : 0;
;       GLOAD(pa, pb, k0)
;     }
;     __builtin_amdgcn_sched_barrier(0);
;     GCOMPUTE(As0, Bs0)
;     __builtin_amdgcn_sched_barrier(0);
;   }
;   __syncthreads();
;   __builtin_amdgcn_sched_barrier(0);
;   GCOMPUTE(As1, Bs1)
;   __builtin_amdgcn_sched_barrier(0);
;   }
;   __syncthreads();
;   GSTORE(As0, Bs0)
	s_setprio 1
	v_mfma_f32_16x16x32_bf16 v[70:73], v[238:241], v[212:215], v[70:73]
	v_mfma_f32_16x16x32_bf16 v[74:77], v[238:241], v[216:219], v[74:77]
	v_mfma_f32_16x16x32_bf16 v[78:81], v[238:241], v[220:223], v[78:81]
	v_mfma_f32_16x16x32_bf16 v[82:85], v[238:241], v[234:237], v[82:85]
	v_mfma_f32_16x16x32_bf16 v[86:89], v[242:245], v[212:215], v[86:89]
	v_mfma_f32_16x16x32_bf16 v[90:93], v[242:245], v[216:219], v[90:93]
	v_mfma_f32_16x16x32_bf16 v[94:97], v[242:245], v[220:223], v[94:97]
	v_mfma_f32_16x16x32_bf16 v[98:101], v[242:245], v[234:237], v[98:101]
	v_mfma_f32_16x16x32_bf16 v[102:105], v[246:249], v[212:215], v[102:105]
	v_mfma_f32_16x16x32_bf16 v[106:109], v[246:249], v[216:219], v[106:109]
	v_mfma_f32_16x16x32_bf16 v[110:113], v[246:249], v[220:223], v[110:113]
	v_mfma_f32_16x16x32_bf16 v[114:117], v[246:249], v[234:237], v[114:117]
	v_mfma_f32_16x16x32_bf16 v[118:121], v[250:253], v[212:215], v[118:121]
	v_mfma_f32_16x16x32_bf16 v[122:125], v[250:253], v[216:219], v[122:125]
	v_mfma_f32_16x16x32_bf16 v[126:129], v[250:253], v[220:223], v[126:129]
	v_mfma_f32_16x16x32_bf16 v[2:5], v[250:253], v[234:237], v[2:5]
	s_setprio 0
	s_barrier
	ds_read_b128 v[162:165], v206 offset:32768
	ds_read_b128 v[166:169], v206 offset:34816
	ds_read_b128 v[170:173], v206 offset:36864
	ds_read_b128 v[174:177], v206 offset:38912
	ds_read_b128 v[238:241], v207
	ds_read_b128 v[242:245], v207 offset:2048
	ds_read_b128 v[246:249], v207 offset:4096
	ds_read_b128 v[250:253], v207 offset:6144
	global_load_dwordx4 v[146:149], v196, s[62:63]
	global_load_dwordx4 v[150:153], v208, s[62:63]
	s_waitcnt vmcnt(9)
	ds_write_b128 v203, v[178:181]
	s_waitcnt vmcnt(8)
	ds_write_b128 v230, v[182:185]
	s_waitcnt lgkmcnt(0)
	s_barrier
	s_setprio 1
	v_mfma_f32_16x16x32_bf16 v[6:9], v[238:241], v[162:165], v[6:9]
	v_mfma_f32_16x16x32_bf16 v[10:13], v[238:241], v[166:169], v[10:13]
	v_mfma_f32_16x16x32_bf16 v[14:17], v[238:241], v[170:173], v[14:17]
	v_mfma_f32_16x16x32_bf16 v[18:21], v[238:241], v[174:177], v[18:21]
	v_mfma_f32_16x16x32_bf16 v[22:25], v[242:245], v[162:165], v[22:25]
	v_mfma_f32_16x16x32_bf16 v[26:29], v[242:245], v[166:169], v[26:29]
	v_mfma_f32_16x16x32_bf16 v[30:33], v[242:245], v[170:173], v[30:33]
	v_mfma_f32_16x16x32_bf16 v[34:37], v[242:245], v[174:177], v[34:37]
	v_mfma_f32_16x16x32_bf16 v[38:41], v[246:249], v[162:165], v[38:41]
	v_mfma_f32_16x16x32_bf16 v[42:45], v[246:249], v[166:169], v[42:45]
	v_mfma_f32_16x16x32_bf16 v[46:49], v[246:249], v[170:173], v[46:49]
	v_mfma_f32_16x16x32_bf16 v[50:53], v[246:249], v[174:177], v[50:53]
	v_mfma_f32_16x16x32_bf16 v[54:57], v[250:253], v[162:165], v[54:57]
	v_mfma_f32_16x16x32_bf16 v[58:61], v[250:253], v[166:169], v[58:61]
	v_mfma_f32_16x16x32_bf16 v[62:65], v[250:253], v[170:173], v[62:65]
	v_mfma_f32_16x16x32_bf16 v[66:69], v[250:253], v[174:177], v[66:69]
	s_setprio 0
	s_barrier
	ds_read_b128 v[238:241], v207 offset:8192
	ds_read_b128 v[242:245], v207 offset:10240
	ds_read_b128 v[246:249], v207 offset:12288
	ds_read_b128 v[250:253], v207 offset:14336
	global_load_dwordx4 v[154:157], v209, s[62:63]
	global_load_dwordx4 v[158:161], v210, s[62:63]
	s_waitcnt vmcnt(9)
	ds_write_b128 v231, v[186:189]
	s_waitcnt vmcnt(8)
	ds_write_b128 v232, v[190:193]
	s_waitcnt lgkmcnt(0)
	s_barrier
	s_setprio 1
	v_mfma_f32_16x16x32_bf16 v[70:73], v[238:241], v[162:165], v[70:73]
	v_mfma_f32_16x16x32_bf16 v[74:77], v[238:241], v[166:169], v[74:77]
	v_mfma_f32_16x16x32_bf16 v[78:81], v[238:241], v[170:173], v[78:81]
	v_mfma_f32_16x16x32_bf16 v[82:85], v[238:241], v[174:177], v[82:85]
	v_mfma_f32_16x16x32_bf16 v[86:89], v[242:245], v[162:165], v[86:89]
	v_mfma_f32_16x16x32_bf16 v[90:93], v[242:245], v[166:169], v[90:93]
	v_mfma_f32_16x16x32_bf16 v[94:97], v[242:245], v[170:173], v[94:97]
	v_mfma_f32_16x16x32_bf16 v[98:101], v[242:245], v[174:177], v[98:101]
	v_mfma_f32_16x16x32_bf16 v[102:105], v[246:249], v[162:165], v[102:105]
	v_mfma_f32_16x16x32_bf16 v[106:109], v[246:249], v[166:169], v[106:109]
	v_mfma_f32_16x16x32_bf16 v[110:113], v[246:249], v[170:173], v[110:113]
	v_mfma_f32_16x16x32_bf16 v[114:117], v[246:249], v[174:177], v[114:117]
	v_mfma_f32_16x16x32_bf16 v[118:121], v[250:253], v[162:165], v[118:121]
	v_mfma_f32_16x16x32_bf16 v[122:125], v[250:253], v[166:169], v[122:125]
	v_mfma_f32_16x16x32_bf16 v[126:129], v[250:253], v[170:173], v[126:129]
	v_mfma_f32_16x16x32_bf16 v[2:5], v[250:253], v[174:177], v[2:5]
	s_setprio 0
	s_barrier
	s_addk_i32 s47, 0x80
	s_add_u32 s44, s44, 0x100
	s_addc_u32 s45, s45, 0
	s_add_u32 s42, s42, 0x100
	s_addc_u32 s43, s43, 0
	s_cmp_gt_u32 s49, 12
	s_mov_b32 s49, s48
	s_cbranch_scc0 .LBB0_82
	ds_read_b128 v[212:215], v198
	ds_read_b128 v[216:219], v198 offset:2048
	ds_read_b128 v[220:223], v198 offset:4096
	ds_read_b128 v[234:237], v198 offset:6144
	ds_read_b128 v[238:241], v199
	ds_read_b128 v[242:245], v199 offset:2048
	ds_read_b128 v[246:249], v199 offset:4096
	ds_read_b128 v[250:253], v199 offset:6144
	s_waitcnt vmcnt(7)
	ds_write_b128 v201, v[130:133]
	s_waitcnt vmcnt(6)
	ds_write_b128 v201, v[134:137] offset:8192
	s_waitcnt lgkmcnt(0)
	s_barrier
; #define GCOMPUTE(AS, BS) GCOMPUTE_KS(AS, BS, 0) GCOMPUTE_KS(AS, BS, 1)
; template <int EPI>
; DI void gemm_phase(const P& p, int l, const u16* __restrict__ A, const u16* __restrict__ Bt, int mpx, char* lds) {
;     ...
;   __syncthreads();
;   __builtin_amdgcn_sched_barrier(0);
;   GCOMPUTE(As1, Bs1)
;   __builtin_amdgcn_sched_barrier(0);
;   }
;   __syncthreads();
;   GSTORE(As0, Bs0)
;     ...
;     const int cb = n0 + wn * 64;
;     const bool isctx = m0 >= MLAT;
;     const int b = isctx ? ((m0 - MLAT) >> 8) : (m0 >> 11);
;     const int tokw = (isctx ? 2048 + ((m0 - MLAT) & 255) : (m0 & 2047)) + wm * 128;
;     u16* Tl = (u16*)(lds + 65536) + w * (64 * 72);
;     int kind = 0;
;     int tr = 0;
;     bool donorm = false;
;     if (cb >= 2816) { kind = 2; tr = 1; }
;     else if (cb < 256) tr = 1;
;     else if (cb < 512) tr = 0;
;     else if (cb < 1024) tr = 2;
;     else if (cb < 1408) { tr = 3; donorm = true; }
;     else if (cb < 1536) kind = 1;
;     else if (cb < 2048) tr = isctx ? 0 : 4;
;     else if (cb < 2304) kind = 1;
;     else if (cb < 2688) tr = isctx ? 0 : 3;
;     else kind = 1;
	s_setprio 1
	v_mfma_f32_16x16x32_bf16 v[6:9], v[238:241], v[212:215], v[6:9]
	v_mfma_f32_16x16x32_bf16 v[10:13], v[238:241], v[216:219], v[10:13]
	v_mfma_f32_16x16x32_bf16 v[14:17], v[238:241], v[220:223], v[14:17]
	v_mfma_f32_16x16x32_bf16 v[18:21], v[238:241], v[234:237], v[18:21]
	v_mfma_f32_16x16x32_bf16 v[22:25], v[242:245], v[212:215], v[22:25]
	v_mfma_f32_16x16x32_bf16 v[26:29], v[242:245], v[216:219], v[26:29]
	v_mfma_f32_16x16x32_bf16 v[30:33], v[242:245], v[220:223], v[30:33]
	v_mfma_f32_16x16x32_bf16 v[34:37], v[242:245], v[234:237], v[34:37]
	v_mfma_f32_16x16x32_bf16 v[38:41], v[246:249], v[212:215], v[38:41]
	v_mfma_f32_16x16x32_bf16 v[42:45], v[246:249], v[216:219], v[42:45]
	v_mfma_f32_16x16x32_bf16 v[46:49], v[246:249], v[220:223], v[46:49]
	v_mfma_f32_16x16x32_bf16 v[50:53], v[246:249], v[234:237], v[50:53]
	v_mfma_f32_16x16x32_bf16 v[54:57], v[250:253], v[212:215], v[54:57]
	v_mfma_f32_16x16x32_bf16 v[58:61], v[250:253], v[216:219], v[58:61]
	v_mfma_f32_16x16x32_bf16 v[62:65], v[250:253], v[220:223], v[62:65]
	v_mfma_f32_16x16x32_bf16 v[66:69], v[250:253], v[234:237], v[66:69]
	s_setprio 0
	s_barrier
	ds_read_b128 v[238:241], v199 offset:8192
	ds_read_b128 v[242:245], v199 offset:10240
	ds_read_b128 v[246:249], v199 offset:12288
	ds_read_b128 v[250:253], v199 offset:14336
	s_waitcnt vmcnt(5)
	ds_write_b128 v201, v[138:141] offset:16384
	s_waitcnt vmcnt(4)
	ds_write_b128 v201, v[142:145] offset:24576
	s_waitcnt lgkmcnt(0)
	s_barrier
	s_setprio 1
	v_mfma_f32_16x16x32_bf16 v[70:73], v[238:241], v[212:215], v[70:73]
	v_mfma_f32_16x16x32_bf16 v[74:77], v[238:241], v[216:219], v[74:77]
	v_mfma_f32_16x16x32_bf16 v[78:81], v[238:241], v[220:223], v[78:81]
	v_mfma_f32_16x16x32_bf16 v[82:85], v[238:241], v[234:237], v[82:85]
	v_mfma_f32_16x16x32_bf16 v[86:89], v[242:245], v[212:215], v[86:89]
	v_mfma_f32_16x16x32_bf16 v[90:93], v[242:245], v[216:219], v[90:93]
	v_mfma_f32_16x16x32_bf16 v[94:97], v[242:245], v[220:223], v[94:97]
	v_mfma_f32_16x16x32_bf16 v[98:101], v[242:245], v[234:237], v[98:101]
	v_mfma_f32_16x16x32_bf16 v[102:105], v[246:249], v[212:215], v[102:105]
	v_mfma_f32_16x16x32_bf16 v[106:109], v[246:249], v[216:219], v[106:109]
	v_mfma_f32_16x16x32_bf16 v[110:113], v[246:249], v[220:223], v[110:113]
	v_mfma_f32_16x16x32_bf16 v[114:117], v[246:249], v[234:237], v[114:117]
	v_mfma_f32_16x16x32_bf16 v[118:121], v[250:253], v[212:215], v[118:121]
	v_mfma_f32_16x16x32_bf16 v[122:125], v[250:253], v[216:219], v[122:125]
	v_mfma_f32_16x16x32_bf16 v[126:129], v[250:253], v[220:223], v[126:129]
	v_mfma_f32_16x16x32_bf16 v[2:5], v[250:253], v[234:237], v[2:5]
	s_setprio 0
	s_barrier
	ds_read_b128 v[130:133], v200
	ds_read_b128 v[134:137], v200 offset:2048
	ds_read_b128 v[138:141], v200 offset:4096
	ds_read_b128 v[142:145], v200 offset:6144
	ds_read_b128 v[238:241], v233
	ds_read_b128 v[242:245], v233 offset:2048
	ds_read_b128 v[246:249], v233 offset:4096
	ds_read_b128 v[250:253], v233 offset:6144
	s_waitcnt vmcnt(3)
	ds_write_b128 v201, v[146:149] offset:32768
	s_waitcnt vmcnt(2)
	ds_write_b128 v201, v[150:153] offset:40960
	s_waitcnt lgkmcnt(0)
	s_barrier
	s_setprio 1
	v_mfma_f32_16x16x32_bf16 v[6:9], v[238:241], v[130:133], v[6:9]
	v_mfma_f32_16x16x32_bf16 v[10:13], v[238:241], v[134:137], v[10:13]
	v_mfma_f32_16x16x32_bf16 v[14:17], v[238:241], v[138:141], v[14:17]
	v_mfma_f32_16x16x32_bf16 v[18:21], v[238:241], v[142:145], v[18:21]
	v_mfma_f32_16x16x32_bf16 v[22:25], v[242:245], v[130:133], v[22:25]
	v_mfma_f32_16x16x32_bf16 v[26:29], v[242:245], v[134:137], v[26:29]
	v_mfma_f32_16x16x32_bf16 v[30:33], v[242:245], v[138:141], v[30:33]
	v_mfma_f32_16x16x32_bf16 v[34:37], v[242:245], v[142:145], v[34:37]
	v_mfma_f32_16x16x32_bf16 v[38:41], v[246:249], v[130:133], v[38:41]
	v_mfma_f32_16x16x32_bf16 v[42:45], v[246:249], v[134:137], v[42:45]
	v_mfma_f32_16x16x32_bf16 v[46:49], v[246:249], v[138:141], v[46:49]
	v_mfma_f32_16x16x32_bf16 v[50:53], v[246:249], v[142:145], v[50:53]
	v_mfma_f32_16x16x32_bf16 v[54:57], v[250:253], v[130:133], v[54:57]
	v_mfma_f32_16x16x32_bf16 v[58:61], v[250:253], v[134:137], v[58:61]
	v_mfma_f32_16x16x32_bf16 v[62:65], v[250:253], v[138:141], v[62:65]
	v_mfma_f32_16x16x32_bf16 v[66:69], v[250:253], v[142:145], v[66:69]
	s_setprio 0
	s_barrier
	ds_read_b128 v[238:241], v233 offset:8192
	ds_read_b128 v[242:245], v233 offset:10240
	ds_read_b128 v[246:249], v233 offset:12288
	ds_read_b128 v[250:253], v233 offset:14336
	s_waitcnt vmcnt(1)
	ds_write_b128 v201, v[154:157] offset:49152
	s_waitcnt vmcnt(0)
	ds_write_b128 v201, v[158:161] offset:57344
	s_waitcnt lgkmcnt(0)
	s_barrier
	s_setprio 1
	v_mfma_f32_16x16x32_bf16 v[70:73], v[238:241], v[130:133], v[70:73]
	v_mfma_f32_16x16x32_bf16 v[74:77], v[238:241], v[134:137], v[74:77]
	v_mfma_f32_16x16x32_bf16 v[78:81], v[238:241], v[138:141], v[78:81]
	v_mfma_f32_16x16x32_bf16 v[82:85], v[238:241], v[142:145], v[82:85]
	v_mfma_f32_16x16x32_bf16 v[86:89], v[242:245], v[130:133], v[86:89]
	v_mfma_f32_16x16x32_bf16 v[90:93], v[242:245], v[134:137], v[90:93]
	v_mfma_f32_16x16x32_bf16 v[94:97], v[242:245], v[138:141], v[94:97]
	v_mfma_f32_16x16x32_bf16 v[98:101], v[242:245], v[142:145], v[98:101]
	v_mfma_f32_16x16x32_bf16 v[102:105], v[246:249], v[130:133], v[102:105]
	v_mfma_f32_16x16x32_bf16 v[106:109], v[246:249], v[134:137], v[106:109]
	v_mfma_f32_16x16x32_bf16 v[110:113], v[246:249], v[138:141], v[110:113]
	v_mfma_f32_16x16x32_bf16 v[114:117], v[246:249], v[142:145], v[114:117]
	v_mfma_f32_16x16x32_bf16 v[118:121], v[250:253], v[130:133], v[118:121]
	v_mfma_f32_16x16x32_bf16 v[122:125], v[250:253], v[134:137], v[122:125]
	v_mfma_f32_16x16x32_bf16 v[126:129], v[250:253], v[138:141], v[126:129]
	v_mfma_f32_16x16x32_bf16 v[2:5], v[250:253], v[142:145], v[2:5]
	s_setprio 0
	s_barrier
	v_readfirstlane_b32 s71, v195
	s_cmp_lt_u32 s71, 0x100
	s_cbranch_scc0 .Lhb_in1
	s_barrier
.Lhb_in1:
	s_nop 0
	v_readfirstlane_b32 s40, v195
	s_lshr_b32 s40, s40, 6
	s_and_b32 s41, s40, 3
	s_lshr_b32 s42, s40, 2
	s_lshr_b32 s43, s46, 6
	s_add_i32 s43, s43, s41
	s_cmp_ge_u32 s66, 0x8000
	s_cselect_b32 s67, 1, 0
	s_mov_b32 s44, 0xffff
	s_mov_b32 s45, 0
	s_bitcmp1_b64 s[44:45], s43
	s_cbranch_scc1 .Lfe_kind0
	s_mov_b32 s44, 0xc00000
	s_mov_b32 s45, 0xc0f
	s_bitcmp1_b64 s[44:45], s43
	s_cbranch_scc1 .Lfe_kind1
	s_cmp_ge_u32 s43, 44
	s_cbranch_scc1 .Lfe_kind2
	s_branch .Lfe_kind0
